# static s_setprio 1 for the second half's waves (4-7) during the MLA attention item loop
# baseline (speedup 1.0000x reference)
; DI int vbid() { return (int)blockIdx.x * 2 + half_(); }
; DI int vgrid() { return (int)gridDim.x * 2; }
; DI void phase_mix2(PREF p, int l, unsigned char* ldsb) {
;   for (int it = vbid(); it < 1024; it += vgrid()) {
;     int qb = (it < 512) ? 31 - (it >> 5) : ((it - 512) >> 5);
;     int bh = it & 31, b = bh >> 2, head = bh & 3;
;     attn_item<96, false>(p.Qm + (size_t)b * S_ * 384 + head * 96, 384, p.Km + (size_t)b * S_ * 384 + head * 96, 384,
;                          p.Vmt + (size_t)(b * 4 + head) * 64 * S_, qb, 0.10206207261596577f * LOG2E, 0.f,
;                          p.hb + (size_t)b * S_ * HW + OFF_BZ + head * 64, HW, p.ys + (size_t)b * S_ * 1024 + 256 + head * 64, 1024,
;                          (u16*)ldsb);
;   }
.LBB0_226:
	s_andn2_b64 vcc, exec, s[10:11]
	v_readlane_b32 s10, v254, 46
	v_readlane_b32 s11, v254, 47
	s_cbranch_vccnz .LBB0_308
	v_readfirstlane_b32 s0, v168
	s_lshr_b32 s0, s0, 8
	s_add_i32 s26, s0, s70
	s_cmpk_gt_i32 s26, 0x3ff
	s_movk_i32 s35, 0x4000
	v_readlane_b32 s36, v254, 23
	s_mov_b32 s37, 0x8000
	s_mov_b32 s40, 0xc000
	s_mov_b32 s41, 0x1ffffc0
	s_mov_b32 s42, 0xfffffc0
	v_readlane_b32 s44, v254, 53
	v_readlane_b32 s45, v254, 54
	s_cbranch_scc1 .LBB0_263
	v_readfirstlane_b32 s98, v168
	s_lshr_b32 s98, s98, 8
	s_cmp_eq_u32 s98, 0
	s_cbranch_scc1 .Lmy_prio_skip
	s_setprio 1
.Lmy_prio_skip:
	v_readlane_b32 s0, v254, 46
	v_readlane_b32 s1, v254, 47
	s_load_dwordx4 s[12:15], s[0:1], 0x140
	s_load_dwordx4 s[16:19], s[0:1], 0x158
	s_load_dwordx2 s[10:11], s[0:1], 0x168
	s_branch .LBB0_230

; DI int tidx() { int t = threadIdx.x & 255; asm volatile("" : "+v"(t)); return t; }
; DI int vbid() { return (int)blockIdx.x * 2 + half_(); }
; DI int vgrid() { return (int)gridDim.x * 2; }
; DI void pw2_tile(PREF p, int l, int idx, unsigned char* ldsb) {
;   u16* lds = (u16*)ldsb; float* Cs = (float*)ldsb;
;   const int tid = tidx();
;   const int mt = idx >> 1, nt = idx & 1;
;   const int row0 = mt * 128, col0 = nt * 128;
;   f32x4 acc[4][4]; zero_acc(acc);
;   gemm_main(acc, p.cA + (size_t)row0 * 256, 256, p.wts + (size_t)l * WL + O_PW2 + (size_t)col0 * 256, 256, 256, lds);
; DI void phase_mix2(PREF p, int l, unsigned char* ldsb) {
;     ...
;   for (int it = vbid(); it < 512; it += vgrid()) pw2_tile(p, l, it, ldsb);
.LBB0_263:
	s_setprio 0
	v_readfirstlane_b32 s0, v168
	s_lshr_b32 s14, s0, 8
	s_add_i32 s16, s14, s70
	s_cmpk_gt_i32 s16, 0x1ff
	s_cbranch_scc1 .LBB0_266
	v_readlane_b32 s12, v254, 46
	v_readlane_b32 s13, v254, 47
	s_load_dwordx2 s[0:1], s[12:13], 0x100
	s_load_dwordx4 s[8:11], s[12:13], 0x140
	s_nop 0
	s_load_dwordx2 s[12:13], s[12:13], 0x150
	s_mul_i32 s17, s44, 0x14b0000
	s_mul_hi_i32 s15, s44, 0x14b0000
	s_waitcnt lgkmcnt(0)
	s_add_u32 s0, s0, s17
	s_addc_u32 s1, s1, s15
	s_add_u32 s17, s0, 0xd80000
	s_addc_u32 s18, s1, 0
	s_lshl_b32 s0, s14, 7
	v_readlane_b32 s1, v254, 22
	s_add_i32 s19, s1, s0
	s_lshl_b32 s0, s14, 6
	s_add_i32 s20, s81, s0
